# mod_reduce: 9 dependent global loads per element issued together (one wait, same add order); retention unit prologue: store-drain wait before next unit loads removed
# baseline (speedup 1.0000x reference)
.LBB0_97:
	v_mul_hi_i32 v1, v0, s7
	v_add_u32_e32 v1, v1, v0
	v_lshrrev_b32_e32 v4, 31, v1
	v_ashrrev_i32_e32 v1, 14, v1
	v_add_u32_e32 v1, v1, v4
	v_mul_hi_i32 v4, v0, s9
	v_lshrrev_b32_e32 v5, 31, v4
	v_ashrrev_i32_e32 v4, 10, v4
	v_add_u32_e32 v4, v4, v5
	v_mul_i32_i24_e32 v4, 0x1800, v4
	v_sub_u32_e32 v4, v0, v4
	v_mad_i32_i24 v4, v1, s12, v4
	v_ashrrev_i32_e32 v5, 31, v4
	v_lshl_add_u64 v[4:5], v[4:5], 2, s[54:55]
	global_load_dword v1, v[4:5], off
	global_load_dword v4, v[2:3], off
	v_add_co_u32_e32 v6, vcc, s13, v2
	s_nop 1
	v_addc_co_u32_e32 v7, vcc, 0, v3, vcc
	global_load_dword v6, v[6:7], off
	v_add_co_u32_e32 v8, vcc, s14, v2
	s_nop 1
	v_addc_co_u32_e32 v9, vcc, 0, v3, vcc
	global_load_dword v8, v[8:9], off
	v_add_co_u32_e32 v10, vcc, s15, v2
	s_nop 1
	v_addc_co_u32_e32 v11, vcc, 0, v3, vcc
	global_load_dword v10, v[10:11], off
	v_add_co_u32_e32 v12, vcc, s34, v2
	s_nop 1
	v_addc_co_u32_e32 v13, vcc, 0, v3, vcc
	global_load_dword v12, v[12:13], off
	v_add_co_u32_e32 v14, vcc, s35, v2
	s_nop 1
	v_addc_co_u32_e32 v15, vcc, 0, v3, vcc
	global_load_dword v14, v[14:15], off
	v_add_co_u32_e32 v16, vcc, s36, v2
	s_nop 1
	v_addc_co_u32_e32 v17, vcc, 0, v3, vcc
	global_load_dword v16, v[16:17], off
	v_add_co_u32_e32 v18, vcc, 0x348000, v2
	s_nop 1
	v_addc_co_u32_e32 v19, vcc, 0, v3, vcc
	global_load_dword v18, v[18:19], off
	v_add_u32_e32 v0, s8, v0
	s_mov_b32 s6, 0x1dfff
	s_waitcnt vmcnt(0)
	v_add_f32_e32 v1, v1, v4
	v_add_f32_e32 v1, v1, v6
	v_add_f32_e32 v1, v1, v8
	v_add_f32_e32 v1, v1, v10
	v_add_f32_e32 v1, v1, v12
	v_add_f32_e32 v1, v1, v14
	v_add_f32_e32 v1, v1, v16
	v_add_f32_e32 v1, v1, v18
	v_add_co_u32_e32 v4, vcc, 0x3c0000, v2
	s_nop 1
	v_addc_co_u32_e32 v5, vcc, 0, v3, vcc
	v_cmp_lt_i32_e32 vcc, s6, v0
	v_lshl_add_u64 v[2:3], v[2:3], 0, s[10:11]
	s_or_b64 s[4:5], vcc, s[4:5]
	global_store_dword v[4:5], v1, off
	s_andn2_b64 exec, exec, s[4:5]
	s_cbranch_execnz .LBB0_97

.LBB0_104:
	v_mul_hi_i32 v1, v0, s7
	v_add_u32_e32 v1, v1, v0
	v_lshrrev_b32_e32 v4, 31, v1
	v_ashrrev_i32_e32 v1, 14, v1
	v_add_u32_e32 v1, v1, v4
	v_mul_hi_i32 v4, v0, s9
	v_lshrrev_b32_e32 v5, 31, v4
	v_ashrrev_i32_e32 v4, 10, v4
	v_add_u32_e32 v4, v4, v5
	v_mul_i32_i24_e32 v4, 0x1800, v4
	v_sub_u32_e32 v4, v0, v4
	v_mad_i32_i24 v4, v1, s12, v4
	v_ashrrev_i32_e32 v5, 31, v4
	v_lshl_add_u64 v[4:5], v[4:5], 2, s[54:55]
	global_load_dword v1, v[4:5], off
	global_load_dword v4, v[2:3], off
	v_add_co_u32_e32 v6, vcc, s13, v2
	s_nop 1
	v_addc_co_u32_e32 v7, vcc, 0, v3, vcc
	global_load_dword v6, v[6:7], off
	v_add_co_u32_e32 v8, vcc, s14, v2
	s_nop 1
	v_addc_co_u32_e32 v9, vcc, 0, v3, vcc
	global_load_dword v8, v[8:9], off
	v_add_co_u32_e32 v10, vcc, s15, v2
	s_nop 1
	v_addc_co_u32_e32 v11, vcc, 0, v3, vcc
	global_load_dword v10, v[10:11], off
	v_add_co_u32_e32 v12, vcc, s34, v2
	s_nop 1
	v_addc_co_u32_e32 v13, vcc, 0, v3, vcc
	global_load_dword v12, v[12:13], off
	v_add_co_u32_e32 v14, vcc, s35, v2
	s_nop 1
	v_addc_co_u32_e32 v15, vcc, 0, v3, vcc
	global_load_dword v14, v[14:15], off
	v_add_co_u32_e32 v16, vcc, s36, v2
	s_nop 1
	v_addc_co_u32_e32 v17, vcc, 0, v3, vcc
	global_load_dword v16, v[16:17], off
	v_add_co_u32_e32 v18, vcc, 0x348000, v2
	s_nop 1
	v_addc_co_u32_e32 v19, vcc, 0, v3, vcc
	global_load_dword v18, v[18:19], off
	v_add_u32_e32 v0, s8, v0
	s_mov_b32 s6, 0x167ff
	s_waitcnt vmcnt(0)
	v_add_f32_e32 v1, v1, v4
	v_add_f32_e32 v1, v1, v6
	v_add_f32_e32 v1, v1, v8
	v_add_f32_e32 v1, v1, v10
	v_add_f32_e32 v1, v1, v12
	v_add_f32_e32 v1, v1, v14
	v_add_f32_e32 v1, v1, v16
	v_add_f32_e32 v1, v1, v18
	v_add_co_u32_e32 v4, vcc, 0x3c0000, v2
	s_nop 1
	v_addc_co_u32_e32 v5, vcc, 0, v3, vcc
	v_cmp_lt_i32_e32 vcc, s6, v0
	v_lshl_add_u64 v[2:3], v[2:3], 0, s[10:11]
	s_or_b64 s[4:5], vcc, s[4:5]
	global_store_dword v[4:5], v1, off
	s_andn2_b64 exec, exec, s[4:5]
	s_cbranch_execnz .LBB0_104

.LBB0_113:
	s_lshr_b32 s6, s40, 2
	s_and_b32 s0, s6, 0x1fffffc0
	s_sub_i32 s7, s0, 64
	s_cmpk_lt_i32 s40, 0x100
	s_cselect_b64 s[0:1], -1, 0
	s_and_b64 s[0:1], s[0:1], exec
	s_cselect_b32 s0, 0, s7
	s_and_b32 s1, s6, 56
	s_or_b32 s41, s0, s1
	s_ashr_i32 s0, s41, 4
	s_lshl_b32 s1, s0, 10
	s_add_i32 s8, s1, 0x1000
	s_lshl_b32 s9, s0, 8
	s_cmpk_lt_i32 s40, 0x100
	s_cselect_b64 s[6:7], -1, 0
	s_and_b64 s[0:1], s[6:7], exec
	s_cselect_b32 s45, 8, 2
	s_cselect_b32 s48, s8, s9
	s_cmpk_gt_i32 s40, 0xff
	s_cselect_b64 s[8:9], -1, 0
	s_and_b32 s0, s40, 6
	s_or_b32 s0, s41, s0
	s_bfe_u32 s1, s40, 0x10005
	s_bfe_i32 s12, s40, 0x10005
	s_and_b32 s44, s40, 7
	s_cmp_eq_u32 s1, 0
	s_cselect_b64 s[0:1], -1, 0
	v_readlane_b32 s80, v252, 40
	s_and_b64 s[10:11], s[0:1], exec
	v_readlane_b32 s88, v252, 48
	v_readlane_b32 s89, v252, 49
	v_readlane_b32 s90, v252, 50
	v_readlane_b32 s91, v252, 51
	s_cselect_b32 s13, s89, s91
	s_cselect_b32 s14, s88, s90
	s_or_b32 s10, s44, s36
	s_ashr_i32 s11, s10, 31
	s_lshl_b64 s[10:11], s[10:11], 2
	s_add_u32 s10, s14, s10
	s_addc_u32 s11, s13, s11
	s_add_i32 s49, s45, -1
	global_load_dword v104, v145, s[10:11]
	s_lshl_b32 s10, s49, 7
	v_sub_u32_e32 v0, 0x7f, v149
	s_and_b32 s10, s12, s10
	v_cndmask_b32_e64 v236, v0, v149, s[0:1]
	s_add_i32 s14, s48, s10
	v_add_u32_e32 v0, s14, v236
	v_mov_b64_e32 v[16:17], s[42:43]
	v_sub_u32_e32 v2, 0x7f, v191
	v_mad_i64_i32 v[0:1], s[10:11], v0, s69, v[16:17]
	s_lshl_b32 s46, s44, 9
	v_cndmask_b32_e64 v237, v2, v191, s[0:1]
	v_lshl_add_u64 v[0:1], v[0:1], 0, s[46:47]
	v_add_u32_e32 v2, s14, v237
	v_sub_u32_e32 v8, 0x7f, v192
	v_lshl_add_u64 v[0:1], v[0:1], 0, v[144:145]
	v_mad_i64_i32 v[2:3], s[10:11], v2, s69, v[16:17]
	v_cndmask_b32_e64 v238, v8, v192, s[0:1]
	v_add_co_u32_e32 v0, vcc, s68, v0
	v_lshl_add_u64 v[2:3], v[2:3], 0, s[46:47]
	v_add_u32_e32 v8, s14, v238
	v_addc_co_u32_e32 v1, vcc, 0, v1, vcc
	v_lshl_add_u64 v[2:3], v[2:3], 0, v[144:145]
	v_mad_i64_i32 v[8:9], s[10:11], v8, s69, v[16:17]
	v_cndmask_b32_e64 v239, v194, v193, s[0:1]
	v_add_co_u32_e32 v4, vcc, s68, v2
	v_lshl_add_u64 v[8:9], v[8:9], 0, s[46:47]
	v_add_u32_e32 v10, s14, v239
	v_addc_co_u32_e32 v5, vcc, 0, v3, vcc
	v_lshl_add_u64 v[8:9], v[8:9], 0, v[144:145]
	v_mad_i64_i32 v[10:11], s[10:11], v10, s69, v[16:17]
	v_cndmask_b32_e64 v240, v196, v195, s[0:1]
	v_add_co_u32_e32 v8, vcc, s68, v8
	v_lshl_add_u64 v[10:11], v[10:11], 0, s[46:47]
	v_add_u32_e32 v18, s14, v240
	v_addc_co_u32_e32 v9, vcc, 0, v9, vcc
	v_lshl_add_u64 v[10:11], v[10:11], 0, v[144:145]
	v_mad_i64_i32 v[18:19], s[10:11], v18, s69, v[16:17]
	v_cndmask_b32_e64 v241, v198, v197, s[0:1]
	v_add_co_u32_e32 v12, vcc, s68, v10
	v_lshl_add_u64 v[18:19], v[18:19], 0, s[46:47]
	v_add_u32_e32 v20, s14, v241
	v_addc_co_u32_e32 v13, vcc, 0, v11, vcc
	v_lshl_add_u64 v[18:19], v[18:19], 0, v[144:145]
	v_mad_i64_i32 v[20:21], s[10:11], v20, s69, v[16:17]
	v_add_co_u32_e32 v18, vcc, s68, v18
	v_lshl_add_u64 v[20:21], v[20:21], 0, s[46:47]
	s_nop 0
	v_addc_co_u32_e32 v19, vcc, 0, v19, vcc
	v_lshl_add_u64 v[20:21], v[20:21], 0, v[144:145]
	v_add_co_u32_e32 v20, vcc, s68, v20
	v_cndmask_b32_e64 v242, v200, v199, s[0:1]
	global_load_dwordx4 v[0:3], v[0:1], off
	s_nop 0
	global_load_dwordx4 v[4:7], v[4:5], off
	s_nop 0
	global_load_dwordx4 v[8:11], v[8:9], off
	s_nop 0
	global_load_dwordx4 v[12:15], v[12:13], off
	v_addc_co_u32_e32 v21, vcc, 0, v21, vcc
	global_load_dwordx4 v[28:31], v[18:19], off
	global_load_dwordx4 v[44:47], v[20:21], off
	v_add_u32_e32 v18, s14, v242
	v_mad_i64_i32 v[18:19], s[10:11], v18, s69, v[16:17]
	v_cndmask_b32_e64 v243, v202, v201, s[0:1]
	v_lshl_add_u64 v[18:19], v[18:19], 0, s[46:47]
	v_add_u32_e32 v20, s14, v243
	v_lshl_add_u64 v[18:19], v[18:19], 0, v[144:145]
	v_mad_i64_i32 v[20:21], s[10:11], v20, s69, v[16:17]
	v_add_co_u32_e32 v18, vcc, s68, v18
	v_lshl_add_u64 v[20:21], v[20:21], 0, s[46:47]
	s_nop 0
	v_addc_co_u32_e32 v19, vcc, 0, v19, vcc
	v_lshl_add_u64 v[20:21], v[20:21], 0, v[144:145]
	v_add_co_u32_e32 v20, vcc, s68, v20
	v_cndmask_b32_e64 v244, v204, v203, s[0:1]
	s_nop 0
	v_addc_co_u32_e32 v21, vcc, 0, v21, vcc
	global_load_dwordx4 v[56:59], v[18:19], off
	global_load_dwordx4 v[60:63], v[20:21], off
	s_lshl_b32 s10, s40, 3
	v_add_u32_e32 v18, s14, v244
	s_and_b32 s50, s10, 0xc0
	v_mad_i64_i32 v[18:19], s[10:11], v18, s69, v[16:17]
	v_cndmask_b32_e64 v245, v206, v205, s[0:1]
	v_lshl_add_u64 v[18:19], v[18:19], 0, s[46:47]
	s_lshl_b32 s10, s50, 1
	s_mov_b32 s11, s47
	v_add_u32_e32 v20, s14, v245
	v_lshl_add_u64 v[18:19], v[18:19], 0, s[10:11]
	v_mov_b32_e32 v157, v145
	v_mad_i64_i32 v[20:21], s[12:13], v20, s69, v[16:17]
	v_lshl_add_u64 v[18:19], v[18:19], 0, v[156:157]
	s_movk_i32 s15, 0x2000
	v_lshl_add_u64 v[20:21], v[20:21], 0, s[46:47]
	v_add_co_u32_e32 v18, vcc, s15, v18
	v_lshl_add_u64 v[20:21], v[20:21], 0, s[10:11]
	s_nop 0
	v_addc_co_u32_e32 v19, vcc, 0, v19, vcc
	v_lshl_add_u64 v[20:21], v[20:21], 0, v[156:157]
	v_add_co_u32_e32 v20, vcc, s15, v20
	v_mov_b32_e32 v155, v145
	s_nop 0
	v_addc_co_u32_e32 v21, vcc, 0, v21, vcc
	global_load_dwordx4 v[64:67], v[18:19], off nt
	global_load_dwordx4 v[68:71], v[20:21], off nt
	v_sub_u32_e32 v18, 0x7f, v188
	v_cndmask_b32_e64 v105, v18, v188, s[0:1]
	v_add_u32_e32 v18, s14, v105
	v_mad_i64_i32 v[16:17], s[12:13], v18, s69, v[16:17]
	v_lshl_add_u64 v[16:17], v[16:17], 0, s[46:47]
	v_lshl_add_u64 v[52:53], v[16:17], 0, v[154:155]
	global_load_dwordx4 v[16:19], v[52:53], off
	global_load_dwordx4 v[20:23], v[52:53], off offset:64
	global_load_dwordx4 v[24:27], v[52:53], off offset:128
	global_load_dwordx4 v[32:35], v[52:53], off offset:192
	global_load_dwordx4 v[36:39], v[52:53], off offset:256
	global_load_dwordx4 v[40:43], v[52:53], off offset:320
	global_load_dwordx4 v[48:51], v[52:53], off offset:384
	s_nop 0
	global_load_dwordx4 v[52:55], v[52:53], off offset:448
	s_and_b64 vcc, exec, s[8:9]
	v_lshlrev_b32_e32 v158, 2, v146
	v_readlane_b32 s81, v252, 41
	v_readlane_b32 s82, v252, 42
	v_readlane_b32 s83, v252, 43
	v_readlane_b32 s84, v252, 44
	v_readlane_b32 s85, v252, 45
	v_readlane_b32 s86, v252, 46
	v_readlane_b32 s87, v252, 47
	v_readlane_b32 s92, v252, 52
	v_readlane_b32 s93, v252, 53
	v_readlane_b32 s94, v252, 54
	v_readlane_b32 s95, v252, 55
	s_cbranch_vccnz .LBB0_115
	v_readlane_b32 s80, v253, 0
	s_and_b64 s[12:13], s[0:1], exec
	v_readlane_b32 s81, v253, 1
	s_cselect_b32 s11, s31, s81
	s_cselect_b32 s14, s30, s80
	s_and_b32 s12, s41, -16
	s_add_i32 s12, s12, s36
	s_or_b32 s12, s44, s12
	s_ashr_i32 s13, s12, 31
	s_lshl_b64 s[12:13], s[12:13], 18
	s_add_u32 s12, s14, s12
	s_addc_u32 s11, s11, s13
	s_lshl_b32 s13, s50, 2
	s_add_u32 s12, s12, s13
	s_addc_u32 s13, s11, 0
	v_mov_b32_e32 v159, v145
	v_lshl_add_u64 v[72:73], s[12:13], 0, v[158:159]
	v_lshl_add_u64 v[72:73], v[152:153], 2, v[72:73]
	global_load_dwordx4 v[100:103], v[72:73], off nt
	global_load_dwordx4 v[96:99], v[72:73], off offset:64 nt
	global_load_dwordx4 v[92:95], v[72:73], off offset:128 nt
	global_load_dwordx4 v[88:91], v[72:73], off offset:192 nt
	v_add_co_u32_e32 v72, vcc, 0x4000, v72
	v_readlane_b32 s82, v253, 2
	s_nop 0
	v_addc_co_u32_e32 v73, vcc, 0, v73, vcc
	global_load_dwordx4 v[84:87], v[72:73], off nt
	global_load_dwordx4 v[80:83], v[72:73], off offset:64 nt
	global_load_dwordx4 v[76:79], v[72:73], off offset:128 nt
	s_nop 0
	global_load_dwordx4 v[72:75], v[72:73], off offset:192 nt
	v_readlane_b32 s83, v253, 3
	v_readlane_b32 s84, v253, 4
	v_readlane_b32 s85, v253, 5
	v_readlane_b32 s86, v253, 6
	v_readlane_b32 s87, v253, 7
	v_readlane_b32 s88, v253, 8
	v_readlane_b32 s89, v253, 9
	v_readlane_b32 s90, v253, 10
	v_readlane_b32 s91, v253, 11
	v_readlane_b32 s92, v253, 12
	v_readlane_b32 s93, v253, 13
	v_readlane_b32 s94, v253, 14
	v_readlane_b32 s95, v253, 15
	s_branch .LBB0_116
